# v48: attention K-tile prefetch addresses kept as running per-lane addresses (27 VALU per tile -> 3)
# baseline (speedup 1.0000x reference)
.LBB0_3260:
	s_or_b64 exec, exec, s[30:31]
	s_and_b64 s[28:29], s[28:29], exec
	s_cselect_b32 s54, 16, 0x80
	s_add_i32 s24, s54, s34
	s_add_i32 s24, s24, -1
	s_lshr_b32 s55, s24, 6
	s_mul_i32 s35, s35, 0x82000
	s_add_u32 s28, s40, s35
	s_addc_u32 s29, s41, 0
	global_load_dwordx4 v[96:99], v[0:1], off
	v_lshl_add_u64 v[0:1], v[150:151], 1, s[28:29]
	v_lshlrev_b64 v[2:3], 1, v[156:157]
	v_lshl_add_u64 v[174:175], v[0:1], 0, v[2:3]
	v_lshl_add_u64 v[0:1], v[152:153], 1, s[28:29]
	v_lshl_add_u64 v[176:177], v[0:1], 0, v[2:3]
	global_load_dwordx4 v[100:103], v[174:175], off
	global_load_dwordx4 v[104:107], v[176:177], off
	v_lshl_add_u64 v[0:1], v[170:171], 1, s[22:23]
	v_mov_b32_e32 v16, v141
	v_mov_b32_e32 v17, v141
	v_or_b32_e32 v169, s34, v185
	v_mov_b32_e32 v18, v141
	v_mov_b32_e32 v19, v141
	v_mov_b32_e32 v20, v141
	v_mov_b32_e32 v21, v141
	v_mov_b32_e32 v22, v141
	v_mov_b32_e32 v23, v141
	v_mov_b32_e32 v24, v141
	v_mov_b32_e32 v25, v141
	v_mov_b32_e32 v26, v141
	v_mov_b32_e32 v27, v141
	v_mov_b32_e32 v28, v141
	v_mov_b32_e32 v29, v141
	v_mov_b32_e32 v30, v141
	v_mov_b32_e32 v31, v141
	v_lshl_add_u64 v[178:179], v[142:143], 1, v[0:1]
	v_lshl_add_u64 v[180:181], v[144:145], 1, v[0:1]
	v_lshl_add_u64 v[182:183], v[172:173], 1, v[0:1]
	s_waitcnt vmcnt(11)
	v_mov_b64_e32 v[0:1], v[16:17]
	v_lshl_add_u32 v32, v172, 1, v195
	v_add_u32_e32 v218, s53, v210
	v_add_u32_e32 v219, s53, v211
	v_add_u32_e32 v220, s53, v212
	s_mov_b32 s56, 0
	v_mov_b32_e32 v184, 0xff800000
	v_mov_b32_e32 v221, 0
	v_add_u32_e32 v222, 31, v169
	v_mov_b64_e32 v[2:3], v[18:19]
	v_mov_b64_e32 v[4:5], v[20:21]
	v_mov_b64_e32 v[6:7], v[22:23]
	v_mov_b64_e32 v[8:9], v[24:25]
	v_mov_b64_e32 v[10:11], v[26:27]
	v_mov_b64_e32 v[12:13], v[28:29]
	v_mov_b64_e32 v[14:15], v[30:31]
	s_add_i32 s57, s55, 1
	s_mov_b32 s58, 0
	v_mov_b32_e32 v252, v220
	v_mov_b32_e32 v253, v141
	v_lshlrev_b64 v[254:255], 10, v[252:253]
	v_lshlrev_b64 v[252:253], 6, v[252:253]
	v_lshl_add_u64 v[252:253], v[158:159], 0, v[252:253]
	v_lshl_add_u64 v[254:255], v[178:179], 0, v[254:255]
	v_lshl_add_u64 v[252:253], v[252:253], 0, s[26:27]
	v_cndmask_b32_e64 v241, v253, v255, s[2:3]
	v_cndmask_b32_e64 v240, v252, v254, s[2:3]
	v_mov_b32_e32 v246, 0x1000
	v_mov_b32_e32 v247, 0x10000
	v_cndmask_b32_e64 v246, v246, v247, s[2:3]
	v_mov_b32_e32 v247, 0
	v_mov_b32_e32 v252, v219
	v_mov_b32_e32 v253, v141
	v_lshlrev_b64 v[254:255], 10, v[252:253]
	v_lshlrev_b64 v[252:253], 6, v[252:253]
	v_lshl_add_u64 v[252:253], v[160:161], 0, v[252:253]
	v_lshl_add_u64 v[254:255], v[180:181], 0, v[254:255]
	v_lshl_add_u64 v[252:253], v[252:253], 0, s[26:27]
	v_cndmask_b32_e64 v243, v253, v255, s[6:7]
	v_cndmask_b32_e64 v242, v252, v254, s[6:7]
	v_mov_b32_e32 v248, 0x1000
	v_mov_b32_e32 v249, 0x10000
	v_cndmask_b32_e64 v248, v248, v249, s[6:7]
	v_mov_b32_e32 v249, 0
	v_mov_b32_e32 v252, v218
	v_mov_b32_e32 v253, v141
	v_lshlrev_b64 v[254:255], 10, v[252:253]
	v_lshlrev_b64 v[252:253], 6, v[252:253]
	v_lshl_add_u64 v[252:253], v[162:163], 0, v[252:253]
	v_lshl_add_u64 v[254:255], v[182:183], 0, v[254:255]
	v_lshl_add_u64 v[252:253], v[252:253], 0, s[26:27]
	v_cndmask_b32_e64 v245, v253, v255, s[10:11]
	v_cndmask_b32_e64 v244, v252, v254, s[10:11]
	v_mov_b32_e32 v250, 0x1000
	v_mov_b32_e32 v251, 0x10000
	v_cndmask_b32_e64 v250, v250, v251, s[10:11]
	v_mov_b32_e32 v251, 0
	s_waitcnt vmcnt(4)
	ds_write_b128 v191, v[88:91]
	s_waitcnt vmcnt(3)
	ds_write_b128 v193, v[92:95]
	s_waitcnt vmcnt(2)
	ds_write_b128 v32, v[96:99]
	s_waitcnt vmcnt(1)
	ds_write2_b64 v214, v[100:101], v[102:103] offset1:1
	s_waitcnt vmcnt(0)
	ds_write2_b64 v215, v[104:105], v[106:107] offset1:1
	s_waitcnt lgkmcnt(0)
	s_barrier
	s_branch .LBB0_3262
.LBB0_3261:
	s_add_i32 s56, s56, 64
	v_lshl_add_u64 v[240:241], v[246:247], 0, v[240:241]
	v_lshl_add_u64 v[242:243], v[248:249], 0, v[242:243]
	v_lshl_add_u64 v[244:245], v[250:251], 0, v[244:245]
	s_cmp_eq_u32 s57, s58
	s_waitcnt lgkmcnt(0)
	s_barrier
	s_cbranch_scc1 .LBB0_3272

.LBB0_3265:
	global_load_dwordx4 v[88:91], v[240:241], off
	global_load_dwordx4 v[92:95], v[242:243], off
	s_add_i32 s24, s56, 64
	s_lshl_b64 s[30:31], s[24:25], 1
	global_load_dwordx4 v[96:99], v[244:245], off
	v_lshl_add_u64 v[32:33], v[174:175], 0, s[30:31]
	v_lshl_add_u64 v[34:35], v[176:177], 0, s[30:31]
	global_load_dwordx4 v[100:103], v[32:33], off
	global_load_dwordx4 v[104:107], v[34:35], off
	v_cmp_le_i32_e32 vcc, s56, v222
	s_and_saveexec_b64 s[30:31], vcc
	s_cbranch_execz .LBB0_3264
